# grid barrier: releasing workgroup does not wait for the release atomics to be acknowledged before starting the next phase
# speedup vs baseline: 1.0296x; 1.0027x over previous
.LBB0_9:
	s_or_b64 exec, exec, s[2:3]
.LBB0_10:
	s_or_b64 exec, exec, s[0:1]
	s_mov_b64 s[0:1], 0
	s_waitcnt lgkmcnt(0)
	s_barrier
